# e24: 6 s_nop inside the attention B-loop so that no 8-byte instruction straddles a 64-byte line
# speedup vs baseline: 1.0044x; 1.0044x over previous
; __device__ __forceinline__ int crow(int r, int hi) { return (r & 3) + 8 * (r >> 2) + 4 * hi; }
; __device__ __forceinline__ int crow(int r, int hi) { return (r & 3) + 8 * (r >> 2) + 4 * hi; }
; __device__ __forceinline__ void attn_unit2(const bf16* __restrict__ Qb, const bf16* __restrict__ Kh, const bf16* __restrict__ Vh, bf16* __restrict__ Ob,
;                                            int NT, int lim, int qrow0, const float* lut, char* lds, float* scr) {
;     ...
;       if (j >= 1) {
;         const float* al = al0 + ((j - 1) & 1) * 128;
;         if (__any(al[r32] < 1.f) || __any(al[32 + r32] < 1.f)) {
; #pragma unroll
;           for (int rb = 0; rb < 2; ++rb)
; #pragma unroll
;             for (int d = 0; d < 4; ++d)
; #pragma unroll
;               for (int r = 0; r < 16; ++r) o[rb][d][r] *= al[rb * 32 + crow(r, hi)]; }
.LBB0_435:
	v_add_u32_e32 v201, s15, v140
	ds_read_b128 v[178:181], v201
	ds_read_b128 v[182:185], v201 offset:32
	ds_read_b128 v[186:189], v201 offset:64
	ds_read_b128 v[190:193], v201 offset:96
	s_waitcnt lgkmcnt(0)
	v_pk_mul_f32 v[118:119], v[118:119], v[180:181]
	v_pk_mul_f32 v[120:121], v[120:121], v[182:183]
	v_pk_mul_f32 v[124:125], v[124:125], v[186:187]
	v_pk_mul_f32 v[128:129], v[128:129], v[190:191]
	v_pk_mul_f32 v[130:131], v[130:131], v[192:193]
	s_nop 0
	v_pk_mul_f32 v[126:127], v[126:127], v[188:189]
	v_pk_mul_f32 v[122:123], v[122:123], v[184:185]
	v_pk_mul_f32 v[116:117], v[116:117], v[178:179]
	v_pk_mul_f32 v[112:113], v[112:113], v[190:191]
	v_pk_mul_f32 v[108:109], v[108:109], v[186:187]
	v_pk_mul_f32 v[104:105], v[104:105], v[182:183]
	v_pk_mul_f32 v[114:115], v[114:115], v[192:193]
	v_pk_mul_f32 v[110:111], v[110:111], v[188:189]
	v_pk_mul_f32 v[106:107], v[106:107], v[184:185]
	v_pk_mul_f32 v[102:103], v[102:103], v[180:181]
	v_pk_mul_f32 v[100:101], v[100:101], v[178:179]
	v_pk_mul_f32 v[96:97], v[96:97], v[190:191]
	v_pk_mul_f32 v[92:93], v[92:93], v[186:187]
	v_pk_mul_f32 v[88:89], v[88:89], v[182:183]
	v_pk_mul_f32 v[98:99], v[98:99], v[192:193]
	v_pk_mul_f32 v[94:95], v[94:95], v[188:189]
	v_pk_mul_f32 v[90:91], v[90:91], v[184:185]
	v_pk_mul_f32 v[86:87], v[86:87], v[180:181]
	v_pk_mul_f32 v[84:85], v[84:85], v[178:179]
	v_pk_mul_f32 v[80:81], v[80:81], v[190:191]
	v_pk_mul_f32 v[76:77], v[76:77], v[186:187]
	v_pk_mul_f32 v[72:73], v[72:73], v[182:183]
	v_pk_mul_f32 v[82:83], v[82:83], v[192:193]
	v_pk_mul_f32 v[78:79], v[78:79], v[188:189]
	v_pk_mul_f32 v[74:75], v[74:75], v[184:185]
	v_pk_mul_f32 v[70:71], v[70:71], v[180:181]
	v_pk_mul_f32 v[68:69], v[68:69], v[178:179]
	ds_read_b128 v[178:181], v201 offset:128
	ds_read_b128 v[182:185], v201 offset:160
	ds_read_b128 v[186:189], v201 offset:192
	ds_read_b128 v[190:193], v201 offset:224
	s_waitcnt lgkmcnt(0)
	s_nop 0
	v_pk_mul_f32 v[54:55], v[54:55], v[180:181]
	v_pk_mul_f32 v[56:57], v[56:57], v[182:183]
	v_pk_mul_f32 v[60:61], v[60:61], v[186:187]
	v_pk_mul_f32 v[64:65], v[64:65], v[190:191]
	v_pk_mul_f32 v[66:67], v[66:67], v[192:193]
	v_pk_mul_f32 v[62:63], v[62:63], v[188:189]
	v_pk_mul_f32 v[58:59], v[58:59], v[184:185]
	v_pk_mul_f32 v[52:53], v[52:53], v[178:179]
	v_pk_mul_f32 v[48:49], v[48:49], v[190:191]
	v_pk_mul_f32 v[44:45], v[44:45], v[186:187]
	v_pk_mul_f32 v[40:41], v[40:41], v[182:183]
	v_pk_mul_f32 v[50:51], v[50:51], v[192:193]
	v_pk_mul_f32 v[46:47], v[46:47], v[188:189]
	v_pk_mul_f32 v[42:43], v[42:43], v[184:185]
	v_pk_mul_f32 v[38:39], v[38:39], v[180:181]
	v_pk_mul_f32 v[36:37], v[36:37], v[178:179]
	v_pk_mul_f32 v[32:33], v[32:33], v[190:191]
	v_pk_mul_f32 v[28:29], v[28:29], v[186:187]
	v_pk_mul_f32 v[24:25], v[24:25], v[182:183]
	v_pk_mul_f32 v[34:35], v[34:35], v[192:193]
	v_pk_mul_f32 v[30:31], v[30:31], v[188:189]
	v_pk_mul_f32 v[26:27], v[26:27], v[184:185]
	v_pk_mul_f32 v[22:23], v[22:23], v[180:181]
	v_pk_mul_f32 v[20:21], v[20:21], v[178:179]
	v_pk_mul_f32 v[16:17], v[16:17], v[190:191]
	v_pk_mul_f32 v[12:13], v[12:13], v[186:187]
	v_pk_mul_f32 v[8:9], v[8:9], v[182:183]
	v_pk_mul_f32 v[18:19], v[18:19], v[192:193]
	v_pk_mul_f32 v[14:15], v[14:15], v[188:189]
	v_pk_mul_f32 v[10:11], v[10:11], v[184:185]
	v_pk_mul_f32 v[6:7], v[6:7], v[180:181]
	v_pk_mul_f32 v[4:5], v[4:5], v[178:179]
; #define SBAR() __builtin_amdgcn_sched_barrier(0)
; #define VRD(D0, L) const s16x4 L##0 = tr_read<v_rd_off(D0, 0, 0)>(vb), L##1 = tr_read<v_rd_off(D0, 0, 1)>(vb), L##2 = tr_read<v_rd_off(D0, 1, 0)>(vb), L##3 = tr_read<v_rd_off(D0, 1, 1)>(vb), \
;                          L##4 = tr_read<v_rd_off(D0, 2, 0)>(vb), L##5 = tr_read<v_rd_off(D0, 2, 1)>(vb), L##6 = tr_read<v_rd_off(D0, 3, 0)>(vb), L##7 = tr_read<v_rd_off(D0, 3, 1)>(vb)
; __device__ __forceinline__ void pv_four(f32x16 (&o)[2][4], int vb, bf16x8 pa0, bf16x8 pa1, bf16x8 pa2, bf16x8 pa3, bf16x8 pb0, bf16x8 pb1, bf16x8 pb2, bf16x8 pb3) {
;     ...
;   VRD(0, x); SBAR();
;   VRD(1, y); asm volatile("s_waitcnt lgkmcnt(8)" ::: "memory"); SBAR(); MMA(0, x); SBAR();
;   VRD(2, z); asm volatile("s_waitcnt lgkmcnt(8)" ::: "memory"); SBAR(); MMA(1, y); SBAR();
;   VRD(3, w); asm volatile("s_waitcnt lgkmcnt(8)" ::: "memory"); SBAR(); MMA(2, z); SBAR();
;   asm volatile("s_waitcnt lgkmcnt(0)" ::: "memory"); SBAR(); MMA(3, w);
; __device__ __forceinline__ void attn_unit2(const bf16* __restrict__ Qb, const bf16* __restrict__ Kh, const bf16* __restrict__ Vh, bf16* __restrict__ Ob,
;                                            int NT, int lim, int qrow0, const float* lut, char* lds, float* scr) {
;     ...
;         const char* ps = P0 + ((j - 1) & 1) * 16384 + lane * 16;
;         const bf16x8 pa0 = *(const bf16x8*)(ps), pa1 = *(const bf16x8*)(ps + 1024), pa2 = *(const bf16x8*)(ps + 2048), pa3 = *(const bf16x8*)(ps + 3072);
;         const bf16x8 pb0 = *(const bf16x8*)(ps + 4096), pb1 = *(const bf16x8*)(ps + 4096 + 1024), pb2 = *(const bf16x8*)(ps + 4096 + 2048), pb3 = *(const bf16x8*)(ps + 4096 + 3072);
;         const int vb = vrb + ((j - 1) & 1) * 32768 + ch * 16384;
;         pv_four(o, vb, pa0, pa1, pa2, pa3, pb0, pb1, pb2, pb3);
;       }
;       asm volatile("s_waitcnt vmcnt(0)" ::: "memory");
;       __syncthreads();
.LBB0_436:
	v_lshl_add_u32 v201, s14, 14, v175
	ds_read_b128 v[178:181], v201
	ds_read_b128 v[182:185], v201 offset:1024
	ds_read_b128 v[186:189], v201 offset:2048
	ds_read_b128 v[190:193], v201 offset:3072
	ds_read_b128 v[194:197], v201 offset:4096
	ds_read_b128 v[208:211], v201 offset:5120
	ds_read_b128 v[212:215], v201 offset:6144
	ds_read_b128 v[216:219], v201 offset:7168
	v_lshl_add_u32 v207, s14, 15, v176
	ds_read_b64_tr_b16 v[220:221], v207 offset:0
	ds_read_b64_tr_b16 v[222:223], v207 offset:0x800
	ds_read_b64_tr_b16 v[224:225], v207 offset:0x1000
	ds_read_b64_tr_b16 v[226:227], v207 offset:0x1800
	ds_read_b64_tr_b16 v[228:229], v207 offset:0x2000
	ds_read_b64_tr_b16 v[230:231], v207 offset:0x2800
	ds_read_b64_tr_b16 v[232:233], v207 offset:0x3000
	ds_read_b64_tr_b16 v[234:235], v207 offset:0x3800
	ds_read_b64_tr_b16 v[236:237], v207 offset:0x200
	ds_read_b64_tr_b16 v[238:239], v207 offset:0xa00
	ds_read_b64_tr_b16 v[240:241], v207 offset:0x1200
	ds_read_b64_tr_b16 v[242:243], v207 offset:0x1a00
	ds_read_b64_tr_b16 v[244:245], v207 offset:0x2200
	ds_read_b64_tr_b16 v[246:247], v207 offset:0x2a00
	ds_read_b64_tr_b16 v[248:249], v207 offset:0x3200
	ds_read_b64_tr_b16 v[250:251], v207 offset:0x3a00
	s_add_i32 m0, s23, 0xc000
	s_nop 0
	global_load_lds_dwordx4 v[156:157], off
	s_add_i32 m0, s23, 0xc400
	s_nop 0
	global_load_lds_dwordx4 v[158:159], off
	s_add_i32 m0, s23, 0xc800
	s_nop 0
	global_load_lds_dwordx4 v[164:165], off
	s_add_i32 m0, s23, 0xcc00
	s_nop 0
	global_load_lds_dwordx4 v[252:253], off
	s_waitcnt lgkmcnt(8)
	s_waitcnt lgkmcnt(0)
	v_mfma_f32_32x32x16_bf16 v[116:131], v[178:181], v[220:223], v[116:131]
	v_mfma_f32_32x32x16_bf16 v[52:67], v[194:197], v[220:223], v[52:67]
	v_mfma_f32_32x32x16_bf16 v[116:131], v[182:185], v[224:227], v[116:131]
	v_mfma_f32_32x32x16_bf16 v[52:67], v[208:211], v[224:227], v[52:67]
	v_mfma_f32_32x32x16_bf16 v[116:131], v[186:189], v[228:231], v[116:131]
	v_mfma_f32_32x32x16_bf16 v[52:67], v[212:215], v[228:231], v[52:67]
	v_mfma_f32_32x32x16_bf16 v[116:131], v[190:193], v[232:235], v[116:131]
	v_mfma_f32_32x32x16_bf16 v[52:67], v[216:219], v[232:235], v[52:67]
	ds_read_b64_tr_b16 v[220:221], v207 offset:0x400
	ds_read_b64_tr_b16 v[222:223], v207 offset:0xc00
	ds_read_b64_tr_b16 v[224:225], v207 offset:0x1400
	ds_read_b64_tr_b16 v[226:227], v207 offset:0x1c00
	ds_read_b64_tr_b16 v[228:229], v207 offset:0x2400
	ds_read_b64_tr_b16 v[230:231], v207 offset:0x2c00
	ds_read_b64_tr_b16 v[232:233], v207 offset:0x3400
	ds_read_b64_tr_b16 v[234:235], v207 offset:0x3c00
	s_waitcnt lgkmcnt(8)
	v_mfma_f32_32x32x16_bf16 v[100:115], v[178:181], v[236:239], v[100:115]
	v_mfma_f32_32x32x16_bf16 v[36:51], v[194:197], v[236:239], v[36:51]
	s_nop 0
	v_mfma_f32_32x32x16_bf16 v[100:115], v[182:185], v[240:243], v[100:115]
	v_mfma_f32_32x32x16_bf16 v[36:51], v[208:211], v[240:243], v[36:51]
	v_mfma_f32_32x32x16_bf16 v[100:115], v[186:189], v[244:247], v[100:115]
	v_mfma_f32_32x32x16_bf16 v[36:51], v[212:215], v[244:247], v[36:51]
	v_mfma_f32_32x32x16_bf16 v[100:115], v[190:193], v[248:251], v[100:115]
	v_mfma_f32_32x32x16_bf16 v[36:51], v[216:219], v[248:251], v[36:51]
	ds_read_b64_tr_b16 v[236:237], v207 offset:0x600
	ds_read_b64_tr_b16 v[238:239], v207 offset:0xe00
	ds_read_b64_tr_b16 v[240:241], v207 offset:0x1600
	ds_read_b64_tr_b16 v[242:243], v207 offset:0x1e00
	ds_read_b64_tr_b16 v[244:245], v207 offset:0x2600
	ds_read_b64_tr_b16 v[246:247], v207 offset:0x2e00
	ds_read_b64_tr_b16 v[248:249], v207 offset:0x3600
	ds_read_b64_tr_b16 v[250:251], v207 offset:0x3e00
	s_waitcnt lgkmcnt(8)
	v_mfma_f32_32x32x16_bf16 v[84:99], v[178:181], v[220:223], v[84:99]
	s_nop 0
	v_mfma_f32_32x32x16_bf16 v[20:35], v[194:197], v[220:223], v[20:35]
	v_mfma_f32_32x32x16_bf16 v[84:99], v[182:185], v[224:227], v[84:99]
	v_mfma_f32_32x32x16_bf16 v[20:35], v[208:211], v[224:227], v[20:35]
	v_mfma_f32_32x32x16_bf16 v[84:99], v[186:189], v[228:231], v[84:99]
	v_mfma_f32_32x32x16_bf16 v[20:35], v[212:215], v[228:231], v[20:35]
	v_mfma_f32_32x32x16_bf16 v[84:99], v[190:193], v[232:235], v[84:99]
	v_mfma_f32_32x32x16_bf16 v[20:35], v[216:219], v[232:235], v[20:35]
	s_waitcnt lgkmcnt(0)
	s_nop 0
	v_mfma_f32_32x32x16_bf16 v[68:83], v[178:181], v[236:239], v[68:83]
	s_add_i32 s9, s9, 0x8000
	s_waitcnt vmcnt(0)
	s_add_u32 s36, s36, 0x40000
	s_addc_u32 s37, s37, 0
	s_add_i32 s14, s10, 1
	s_addk_i32 s7, 0x4000
	s_cmp_eq_u32 s8, s36
	v_mfma_f32_32x32x16_bf16 v[4:19], v[194:197], v[236:239], v[4:19]
	s_waitcnt vmcnt(0)
	s_barrier
	s_nop 0
	v_mfma_f32_32x32x16_bf16 v[68:83], v[182:185], v[240:243], v[68:83]
	v_mfma_f32_32x32x16_bf16 v[4:19], v[208:211], v[240:243], v[4:19]
	v_mfma_f32_32x32x16_bf16 v[68:83], v[186:189], v[244:247], v[68:83]
	v_mfma_f32_32x32x16_bf16 v[4:19], v[212:215], v[244:247], v[4:19]
	v_mfma_f32_32x32x16_bf16 v[68:83], v[190:193], v[248:251], v[68:83]
	v_mfma_f32_32x32x16_bf16 v[4:19], v[216:219], v[248:251], v[4:19]
	s_cbranch_scc1 .LBB0_439
	s_mov_b32 s10, s14
	s_cmp_lt_u32 s10, s5
	s_cselect_b64 s[38:39], -1, 0
	s_cmp_ge_u32 s10, s5
	s_cbranch_scc0 .LBB0_432
	s_branch .LBB0_433
